# v113 + local seams: fire-and-forget arrival atomic, first poll issued right behind it, static target 32*k
# speedup vs baseline: 1.0013x; 1.0013x over previous
; __device__ __forceinline__ unsigned xb_ld(unsigned* p)              { return __hip_atomic_load(p, __ATOMIC_RELAXED, __HIP_MEMORY_SCOPE_AGENT); }
; __device__ __forceinline__ unsigned xb_add(unsigned* p, unsigned v) { return __hip_atomic_fetch_add(p, v, __ATOMIC_RELAXED, __HIP_MEMORY_SCOPE_AGENT); }
; #define XB_SPIN(cond, bar) do { unsigned _sp = 0; while (cond) { __builtin_amdgcn_s_sleep(1); \
;     if ((++_sp & 255u) == 0u) { if (xb_ld(&(bar)[XB_TMO])) break; if (_sp > XB_SPIN_CAP) { atomicAdd(&(bar)[XB_TMO], 1u); break; } } } } while (0)
; #define SEAM(k) do { if (IN(k) && IN((k) + 1)) { xcd_barrier(bar, wave == 0 && mk_lane() == 0); } } while (0)
; __device__ __forceinline__ void xcd_barrier(const XcdBarrier& b, bool leader) {
;     asm volatile("s_waitcnt vmcnt(0)" ::: "memory");
;     __syncthreads();
;     if (leader) {
;         unsigned* bar = b.bar;
;         __builtin_amdgcn_s_waitcnt(0);
;         unsigned nloc = b.st[0], nx = b.st[1];
;         if (nloc == 0u) { xcd_barrier_complete(bar, b.x, nloc, nx); b.st[0] = nloc; b.st[1] = nx; }
;         const unsigned old = xb_add(&bar[XB_XSUB(b.x)], 1u);
;         const unsigned gen = old / nloc;
;         if (old + 1u == (gen + 1u) * nloc) {
;             __builtin_amdgcn_fence(__ATOMIC_RELEASE, "agent");
;             asm volatile("s_waitcnt vmcnt(0)" ::: "memory");
;             const unsigned og = xb_add(&bar[XB_TOP], 1u);
;             const unsigned tg = og / nx;
;             if (og + 1u == (tg + 1u) * nx) xb_add(&bar[XB_TOPGEN], 1u);
;             else XB_SPIN(xb_ld(&bar[XB_TOPGEN]) == tg, bar);
;             __builtin_amdgcn_fence(__ATOMIC_ACQUIRE, "agent");
;             xb_add(&bar[XB_XGEN(b.x)], 1u);
;             asm volatile("s_waitcnt vmcnt(0)" ::: "memory");
;         } else {
;             XB_SPIN(xb_ld(&bar[XB_XGEN(b.x)]) == gen, bar);
;             __builtin_amdgcn_fence(__ATOMIC_ACQUIRE, "agent");
;             asm volatile("s_waitcnt vmcnt(0)" ::: "memory");
;         }
;     }
;     __syncthreads();
; }
; __global__ void __launch_bounds__(NWAVES * 64, 2) mk_fwd(Params P) {
;     ...
;           pg8::gemm_phase<pg8::EpiProj, pg8::StaticOrder, true, true>(lds, g, S, E, wave); }
;     }
;     SEAM(1);
.LBB0_463:
	s_waitcnt vmcnt(0)
	s_waitcnt lgkmcnt(0)
	s_barrier
	s_and_saveexec_b64 s[4:5], s[6:7]
	s_cbranch_execz .LBB0_511
	v_readlane_b32 s8, v254, 2
	v_readlane_b32 s9, v254, 3
	s_and_b32 s2, s88, 7
	s_lshl_b32 s2, s2, 8
	s_add_u32 s2, s8, s2
	s_addc_u32 s3, s9, 0
	v_mov_b32_e32 v0, 0
	v_mov_b32_e32 v1, 1
	v_mov_b32_e32 v5, 0x1400
	global_load_dwordx4 v[6:9], v0, s[8:9] offset:768 sc1
	global_load_dwordx4 v[10:13], v0, s[8:9] offset:784 sc1
	global_atomic_add v5, v1, s[2:3] offset:128
	global_load_dword v3, v5, s[2:3] offset:128 sc1
	s_waitcnt vmcnt(2)
	v_add_u32_e32 v14, -1, v6
	v_and_b32_e32 v2, v14, v6
	v_add_u32_e32 v14, -1, v7
	v_and_or_b32 v2, v14, v7, v2
	v_add_u32_e32 v14, -1, v8
	v_and_or_b32 v2, v14, v8, v2
	v_add_u32_e32 v14, -1, v9
	v_and_or_b32 v2, v14, v9, v2
	v_add_u32_e32 v14, -1, v10
	v_and_or_b32 v2, v14, v10, v2
	v_add_u32_e32 v14, -1, v11
	v_and_or_b32 v2, v14, v11, v2
	v_add_u32_e32 v14, -1, v12
	v_and_or_b32 v2, v14, v12, v2
	v_add_u32_e32 v14, -1, v13
	v_and_or_b32 v2, v14, v13, v2
	v_cmp_ne_u32_e32 vcc, 0, v2
	s_cbranch_vccnz .Lmy_glob_k1
	v_mov_b32_e32 v4, 32
	s_waitcnt vmcnt(0)
	v_sub_u32_e32 v2, v3, v4
	v_cmp_gt_i32_e32 vcc, 0, v2
	s_cbranch_vccz .Lmy_done_k1
	s_mov_b32 s10, 0

; __device__ __forceinline__ unsigned xb_ld(unsigned* p)              { return __hip_atomic_load(p, __ATOMIC_RELAXED, __HIP_MEMORY_SCOPE_AGENT); }
; __device__ __forceinline__ unsigned xb_add(unsigned* p, unsigned v) { return __hip_atomic_fetch_add(p, v, __ATOMIC_RELAXED, __HIP_MEMORY_SCOPE_AGENT); }
; #define XB_SPIN(cond, bar) do { unsigned _sp = 0; while (cond) { __builtin_amdgcn_s_sleep(1); \
;     if ((++_sp & 255u) == 0u) { if (xb_ld(&(bar)[XB_TMO])) break; if (_sp > XB_SPIN_CAP) { atomicAdd(&(bar)[XB_TMO], 1u); break; } } } } while (0)
; #define SEAM(k) do { if (IN(k) && IN((k) + 1)) { xcd_barrier(bar, wave == 0 && mk_lane() == 0); } } while (0)
; __device__ __forceinline__ void xcd_barrier(const XcdBarrier& b, bool leader) {
;     asm volatile("s_waitcnt vmcnt(0)" ::: "memory");
;     __syncthreads();
;     if (leader) {
;         unsigned* bar = b.bar;
;         __builtin_amdgcn_s_waitcnt(0);
;         unsigned nloc = b.st[0], nx = b.st[1];
;         if (nloc == 0u) { xcd_barrier_complete(bar, b.x, nloc, nx); b.st[0] = nloc; b.st[1] = nx; }
;         const unsigned old = xb_add(&bar[XB_XSUB(b.x)], 1u);
;         const unsigned gen = old / nloc;
;         if (old + 1u == (gen + 1u) * nloc) {
;             __builtin_amdgcn_fence(__ATOMIC_RELEASE, "agent");
;             asm volatile("s_waitcnt vmcnt(0)" ::: "memory");
;             const unsigned og = xb_add(&bar[XB_TOP], 1u);
;             const unsigned tg = og / nx;
;             if (og + 1u == (tg + 1u) * nx) xb_add(&bar[XB_TOPGEN], 1u);
;             else XB_SPIN(xb_ld(&bar[XB_TOPGEN]) == tg, bar);
;             __builtin_amdgcn_fence(__ATOMIC_ACQUIRE, "agent");
;             xb_add(&bar[XB_XGEN(b.x)], 1u);
;             asm volatile("s_waitcnt vmcnt(0)" ::: "memory");
;         } else {
;             XB_SPIN(xb_ld(&bar[XB_XGEN(b.x)]) == gen, bar);
;             __builtin_amdgcn_fence(__ATOMIC_ACQUIRE, "agent");
;             asm volatile("s_waitcnt vmcnt(0)" ::: "memory");
;         }
;     }
;     __syncthreads();
; }
; __global__ void __launch_bounds__(NWAVES * 64, 2) mk_fwd(Params P) {
;     ...
;         }
;     }
;     SEAM(2);
.LBB0_750:
	s_waitcnt vmcnt(0)
	s_waitcnt lgkmcnt(0)
	s_barrier
	s_and_saveexec_b64 s[4:5], s[6:7]
	s_cbranch_execz .LBB0_798
	v_readlane_b32 s8, v254, 2
	v_readlane_b32 s9, v254, 3
	s_and_b32 s2, s88, 7
	s_lshl_b32 s2, s2, 8
	s_add_u32 s2, s8, s2
	s_addc_u32 s3, s9, 0
	v_mov_b32_e32 v0, 0
	v_mov_b32_e32 v1, 1
	v_mov_b32_e32 v5, 0x1400
	global_load_dwordx4 v[6:9], v0, s[8:9] offset:768 sc1
	global_load_dwordx4 v[10:13], v0, s[8:9] offset:784 sc1
	global_atomic_add v5, v1, s[2:3] offset:128
	global_load_dword v3, v5, s[2:3] offset:128 sc1
	s_waitcnt vmcnt(2)
	v_add_u32_e32 v14, -1, v6
	v_and_b32_e32 v2, v14, v6
	v_add_u32_e32 v14, -1, v7
	v_and_or_b32 v2, v14, v7, v2
	v_add_u32_e32 v14, -1, v8
	v_and_or_b32 v2, v14, v8, v2
	v_add_u32_e32 v14, -1, v9
	v_and_or_b32 v2, v14, v9, v2
	v_add_u32_e32 v14, -1, v10
	v_and_or_b32 v2, v14, v10, v2
	v_add_u32_e32 v14, -1, v11
	v_and_or_b32 v2, v14, v11, v2
	v_add_u32_e32 v14, -1, v12
	v_and_or_b32 v2, v14, v12, v2
	v_add_u32_e32 v14, -1, v13
	v_and_or_b32 v2, v14, v13, v2
	v_cmp_ne_u32_e32 vcc, 0, v2
	s_cbranch_vccnz .Lmy_glob_k2
	v_mov_b32_e32 v4, 64
	s_waitcnt vmcnt(0)
	v_sub_u32_e32 v2, v3, v4
	v_cmp_gt_i32_e32 vcc, 0, v2
	s_cbranch_vccz .Lmy_done_k2
	s_mov_b32 s10, 0

; __device__ __forceinline__ unsigned xb_ld(unsigned* p)              { return __hip_atomic_load(p, __ATOMIC_RELAXED, __HIP_MEMORY_SCOPE_AGENT); }
; __device__ __forceinline__ unsigned xb_add(unsigned* p, unsigned v) { return __hip_atomic_fetch_add(p, v, __ATOMIC_RELAXED, __HIP_MEMORY_SCOPE_AGENT); }
; #define XB_SPIN(cond, bar) do { unsigned _sp = 0; while (cond) { __builtin_amdgcn_s_sleep(1); \
;     if ((++_sp & 255u) == 0u) { if (xb_ld(&(bar)[XB_TMO])) break; if (_sp > XB_SPIN_CAP) { atomicAdd(&(bar)[XB_TMO], 1u); break; } } } } while (0)
; #define SEAM(k) do { if (IN(k) && IN((k) + 1)) { xcd_barrier(bar, wave == 0 && mk_lane() == 0); } } while (0)
; __device__ __forceinline__ void xcd_barrier(const XcdBarrier& b, bool leader) {
;     asm volatile("s_waitcnt vmcnt(0)" ::: "memory");
;     __syncthreads();
;     if (leader) {
;         unsigned* bar = b.bar;
;         __builtin_amdgcn_s_waitcnt(0);
;         unsigned nloc = b.st[0], nx = b.st[1];
;         if (nloc == 0u) { xcd_barrier_complete(bar, b.x, nloc, nx); b.st[0] = nloc; b.st[1] = nx; }
;         const unsigned old = xb_add(&bar[XB_XSUB(b.x)], 1u);
;         const unsigned gen = old / nloc;
;         if (old + 1u == (gen + 1u) * nloc) {
;             __builtin_amdgcn_fence(__ATOMIC_RELEASE, "agent");
;             asm volatile("s_waitcnt vmcnt(0)" ::: "memory");
;             const unsigned og = xb_add(&bar[XB_TOP], 1u);
;             const unsigned tg = og / nx;
;             if (og + 1u == (tg + 1u) * nx) xb_add(&bar[XB_TOPGEN], 1u);
;             else XB_SPIN(xb_ld(&bar[XB_TOPGEN]) == tg, bar);
;             __builtin_amdgcn_fence(__ATOMIC_ACQUIRE, "agent");
;             xb_add(&bar[XB_XGEN(b.x)], 1u);
;             asm volatile("s_waitcnt vmcnt(0)" ::: "memory");
;         } else {
;             XB_SPIN(xb_ld(&bar[XB_XGEN(b.x)]) == gen, bar);
;             __builtin_amdgcn_fence(__ATOMIC_ACQUIRE, "agent");
;             asm volatile("s_waitcnt vmcnt(0)" ::: "memory");
;         }
;     }
;     __syncthreads();
; }
; __global__ void __launch_bounds__(NWAVES * 64, 2) mk_fwd(Params P) {
;     ...
;         }
;     }
;     SEAM(3);
.LBB0_851:
	s_waitcnt vmcnt(0)
	s_waitcnt lgkmcnt(0)
	s_barrier
	s_and_saveexec_b64 s[4:5], s[6:7]
	s_cbranch_execz .LBB0_899
	v_readlane_b32 s8, v254, 2
	v_readlane_b32 s9, v254, 3
	s_and_b32 s2, s88, 7
	s_lshl_b32 s2, s2, 8
	s_add_u32 s2, s8, s2
	s_addc_u32 s3, s9, 0
	v_mov_b32_e32 v0, 0
	v_mov_b32_e32 v1, 1
	v_mov_b32_e32 v5, 0x1400
	global_load_dwordx4 v[6:9], v0, s[8:9] offset:768 sc1
	global_load_dwordx4 v[10:13], v0, s[8:9] offset:784 sc1
	global_atomic_add v5, v1, s[2:3] offset:128
	global_load_dword v3, v5, s[2:3] offset:128 sc1
	s_waitcnt vmcnt(2)
	v_add_u32_e32 v14, -1, v6
	v_and_b32_e32 v2, v14, v6
	v_add_u32_e32 v14, -1, v7
	v_and_or_b32 v2, v14, v7, v2
	v_add_u32_e32 v14, -1, v8
	v_and_or_b32 v2, v14, v8, v2
	v_add_u32_e32 v14, -1, v9
	v_and_or_b32 v2, v14, v9, v2
	v_add_u32_e32 v14, -1, v10
	v_and_or_b32 v2, v14, v10, v2
	v_add_u32_e32 v14, -1, v11
	v_and_or_b32 v2, v14, v11, v2
	v_add_u32_e32 v14, -1, v12
	v_and_or_b32 v2, v14, v12, v2
	v_add_u32_e32 v14, -1, v13
	v_and_or_b32 v2, v14, v13, v2
	v_cmp_ne_u32_e32 vcc, 0, v2
	s_cbranch_vccnz .Lmy_glob_k3
	v_mov_b32_e32 v4, 96
	s_waitcnt vmcnt(0)
	v_sub_u32_e32 v2, v3, v4
	v_cmp_gt_i32_e32 vcc, 0, v2
	s_cbranch_vccz .Lmy_done_k3
	s_mov_b32 s10, 0

; __device__ __forceinline__ unsigned xb_ld(unsigned* p)              { return __hip_atomic_load(p, __ATOMIC_RELAXED, __HIP_MEMORY_SCOPE_AGENT); }
; __device__ __forceinline__ unsigned xb_add(unsigned* p, unsigned v) { return __hip_atomic_fetch_add(p, v, __ATOMIC_RELAXED, __HIP_MEMORY_SCOPE_AGENT); }
; #define XB_SPIN(cond, bar) do { unsigned _sp = 0; while (cond) { __builtin_amdgcn_s_sleep(1); \
;     if ((++_sp & 255u) == 0u) { if (xb_ld(&(bar)[XB_TMO])) break; if (_sp > XB_SPIN_CAP) { atomicAdd(&(bar)[XB_TMO], 1u); break; } } } } while (0)
; #define SEAM(k) do { if (IN(k) && IN((k) + 1)) { xcd_barrier(bar, wave == 0 && mk_lane() == 0); } } while (0)
; __device__ __forceinline__ void xcd_barrier(const XcdBarrier& b, bool leader) {
;     asm volatile("s_waitcnt vmcnt(0)" ::: "memory");
;     __syncthreads();
;     if (leader) {
;         unsigned* bar = b.bar;
;         __builtin_amdgcn_s_waitcnt(0);
;         unsigned nloc = b.st[0], nx = b.st[1];
;         if (nloc == 0u) { xcd_barrier_complete(bar, b.x, nloc, nx); b.st[0] = nloc; b.st[1] = nx; }
;         const unsigned old = xb_add(&bar[XB_XSUB(b.x)], 1u);
;         const unsigned gen = old / nloc;
;         if (old + 1u == (gen + 1u) * nloc) {
;             __builtin_amdgcn_fence(__ATOMIC_RELEASE, "agent");
;             asm volatile("s_waitcnt vmcnt(0)" ::: "memory");
;             const unsigned og = xb_add(&bar[XB_TOP], 1u);
;             const unsigned tg = og / nx;
;             if (og + 1u == (tg + 1u) * nx) xb_add(&bar[XB_TOPGEN], 1u);
;             else XB_SPIN(xb_ld(&bar[XB_TOPGEN]) == tg, bar);
;             __builtin_amdgcn_fence(__ATOMIC_ACQUIRE, "agent");
;             xb_add(&bar[XB_XGEN(b.x)], 1u);
;             asm volatile("s_waitcnt vmcnt(0)" ::: "memory");
;         } else {
;             XB_SPIN(xb_ld(&bar[XB_XGEN(b.x)]) == gen, bar);
;             __builtin_amdgcn_fence(__ATOMIC_ACQUIRE, "agent");
;             asm volatile("s_waitcnt vmcnt(0)" ::: "memory");
;         }
;     }
;     __syncthreads();
; }
; __global__ void __launch_bounds__(NWAVES * 64, 2) mk_fwd(Params P) {
;     ...
;         pg8::EpiRes2<true, true> E{XN, H1B, SS1};
;         pg8::gemm_phase<pg8::EpiRes2<true, true>, pg8::StaticOrder, true, true>(lds, g, S, E, wave); }
;     SEAM(4);
.LBB0_942:
	s_waitcnt vmcnt(0)
	s_waitcnt lgkmcnt(0)
	s_barrier
	s_and_saveexec_b64 s[0:1], s[6:7]
	s_cbranch_execz .LBB0_990
	v_readlane_b32 s8, v254, 2
	v_readlane_b32 s9, v254, 3
	s_and_b32 s2, s88, 7
	s_lshl_b32 s2, s2, 8
	s_add_u32 s2, s8, s2
	s_addc_u32 s3, s9, 0
	v_mov_b32_e32 v0, 0
	v_mov_b32_e32 v1, 1
	v_mov_b32_e32 v5, 0x1400
	global_load_dwordx4 v[6:9], v0, s[8:9] offset:768 sc1
	global_load_dwordx4 v[10:13], v0, s[8:9] offset:784 sc1
	global_atomic_add v5, v1, s[2:3] offset:128
	buffer_inv sc1
	global_load_dword v3, v5, s[2:3] offset:128 sc1
	s_waitcnt vmcnt(3)
	v_add_u32_e32 v14, -1, v6
	v_and_b32_e32 v2, v14, v6
	v_add_u32_e32 v14, -1, v7
	v_and_or_b32 v2, v14, v7, v2
	v_add_u32_e32 v14, -1, v8
	v_and_or_b32 v2, v14, v8, v2
	v_add_u32_e32 v14, -1, v9
	v_and_or_b32 v2, v14, v9, v2
	v_add_u32_e32 v14, -1, v10
	v_and_or_b32 v2, v14, v10, v2
	v_add_u32_e32 v14, -1, v11
	v_and_or_b32 v2, v14, v11, v2
	v_add_u32_e32 v14, -1, v12
	v_and_or_b32 v2, v14, v12, v2
	v_add_u32_e32 v14, -1, v13
	v_and_or_b32 v2, v14, v13, v2
	v_cmp_ne_u32_e32 vcc, 0, v2
	s_cbranch_vccnz .Lmy_glob_k4
	v_mov_b32_e32 v4, 128
	s_waitcnt vmcnt(0)
	v_sub_u32_e32 v2, v3, v4
	v_cmp_gt_i32_e32 vcc, 0, v2
	s_cbranch_vccz .Lmy_done_k4
	s_mov_b32 s10, 0

; #define LAS __attribute__((address_space(3)))
; __device__ __forceinline__ unsigned xb_ld(unsigned* p)              { return __hip_atomic_load(p, __ATOMIC_RELAXED, __HIP_MEMORY_SCOPE_AGENT); }
; __device__ __forceinline__ unsigned xb_add(unsigned* p, unsigned v) { return __hip_atomic_fetch_add(p, v, __ATOMIC_RELAXED, __HIP_MEMORY_SCOPE_AGENT); }
; #define XB_SPIN(cond, bar) do { unsigned _sp = 0; while (cond) { __builtin_amdgcn_s_sleep(1); \
;     if ((++_sp & 255u) == 0u) { if (xb_ld(&(bar)[XB_TMO])) break; if (_sp > XB_SPIN_CAP) { atomicAdd(&(bar)[XB_TMO], 1u); break; } } } } while (0)
; __device__ __forceinline__ void xcd_barrier(const XcdBarrier& b, bool leader) {
;     asm volatile("s_waitcnt vmcnt(0)" ::: "memory");
;     __syncthreads();
;     if (leader) {
;         unsigned* bar = b.bar;
;         __builtin_amdgcn_s_waitcnt(0);
;         unsigned nloc = b.st[0], nx = b.st[1];
;         if (nloc == 0u) { xcd_barrier_complete(bar, b.x, nloc, nx); b.st[0] = nloc; b.st[1] = nx; }
;         const unsigned old = xb_add(&bar[XB_XSUB(b.x)], 1u);
;         const unsigned gen = old / nloc;
;         if (old + 1u == (gen + 1u) * nloc) {
;             __builtin_amdgcn_fence(__ATOMIC_RELEASE, "agent");
;             asm volatile("s_waitcnt vmcnt(0)" ::: "memory");
;             const unsigned og = xb_add(&bar[XB_TOP], 1u);
;             const unsigned tg = og / nx;
;             if (og + 1u == (tg + 1u) * nx) xb_add(&bar[XB_TOPGEN], 1u);
;             else XB_SPIN(xb_ld(&bar[XB_TOPGEN]) == tg, bar);
;             __builtin_amdgcn_fence(__ATOMIC_ACQUIRE, "agent");
;             xb_add(&bar[XB_XGEN(b.x)], 1u);
;             asm volatile("s_waitcnt vmcnt(0)" ::: "memory");
;         } else {
;             XB_SPIN(xb_ld(&bar[XB_XGEN(b.x)]) == gen, bar);
;             __builtin_amdgcn_fence(__ATOMIC_ACQUIRE, "agent");
;             asm volatile("s_waitcnt vmcnt(0)" ::: "memory");
;         }
;     }
;     __syncthreads();
; }
; __global__ void __launch_bounds__(NWAVES * 64, 2) mk_fwd(Params P) {
;     ...
;         pg8::EpiRowScale<0> E{CQ, D, SS1, EPS, pg8::CROSS_C2, (const LAS int*)(lds + RING_BYTES + 1536), (const LAS float*)(lds + RING_BYTES + 2048)};
;         pg8::gemm_phase<pg8::EpiRowScale<0>, pg8::StaticOrder, true, true>(lds, g, S, E, wave); }
;     SEAM(5);
.LBB0_1092:
	s_waitcnt vmcnt(0)
	s_waitcnt vmcnt(0) lgkmcnt(0)
	s_barrier
	s_and_saveexec_b64 s[4:5], s[6:7]
	s_cbranch_execz .LBB0_1140
	v_readlane_b32 s8, v254, 2
	v_readlane_b32 s9, v254, 3
	s_and_b32 s2, s88, 7
	s_lshl_b32 s2, s2, 8
	s_add_u32 s2, s8, s2
	s_addc_u32 s3, s9, 0
	v_mov_b32_e32 v0, 0
	v_mov_b32_e32 v1, 1
	v_mov_b32_e32 v5, 0x1400
	global_load_dwordx4 v[6:9], v0, s[8:9] offset:768 sc1
	global_load_dwordx4 v[10:13], v0, s[8:9] offset:784 sc1
	global_atomic_add v5, v1, s[2:3] offset:128
	global_load_dword v3, v5, s[2:3] offset:128 sc1
	s_waitcnt vmcnt(2)
	v_add_u32_e32 v14, -1, v6
	v_and_b32_e32 v2, v14, v6
	v_add_u32_e32 v14, -1, v7
	v_and_or_b32 v2, v14, v7, v2
	v_add_u32_e32 v14, -1, v8
	v_and_or_b32 v2, v14, v8, v2
	v_add_u32_e32 v14, -1, v9
	v_and_or_b32 v2, v14, v9, v2
	v_add_u32_e32 v14, -1, v10
	v_and_or_b32 v2, v14, v10, v2
	v_add_u32_e32 v14, -1, v11
	v_and_or_b32 v2, v14, v11, v2
	v_add_u32_e32 v14, -1, v12
	v_and_or_b32 v2, v14, v12, v2
	v_add_u32_e32 v14, -1, v13
	v_and_or_b32 v2, v14, v13, v2
	v_cmp_ne_u32_e32 vcc, 0, v2
	s_cbranch_vccnz .Lmy_glob_k5
	v_mov_b32_e32 v4, 160
	s_waitcnt vmcnt(0)
	v_sub_u32_e32 v2, v3, v4
	v_cmp_gt_i32_e32 vcc, 0, v2
	s_cbranch_vccz .Lmy_done_k5
	s_mov_b32 s10, 0

; __device__ __forceinline__ unsigned xb_ld(unsigned* p)              { return __hip_atomic_load(p, __ATOMIC_RELAXED, __HIP_MEMORY_SCOPE_AGENT); }
; __device__ __forceinline__ unsigned xb_add(unsigned* p, unsigned v) { return __hip_atomic_fetch_add(p, v, __ATOMIC_RELAXED, __HIP_MEMORY_SCOPE_AGENT); }
; #define XB_SPIN(cond, bar) do { unsigned _sp = 0; while (cond) { __builtin_amdgcn_s_sleep(1); \
;     if ((++_sp & 255u) == 0u) { if (xb_ld(&(bar)[XB_TMO])) break; if (_sp > XB_SPIN_CAP) { atomicAdd(&(bar)[XB_TMO], 1u); break; } } } } while (0)
; #define SEAM(k) do { if (IN(k) && IN((k) + 1)) { xcd_barrier(bar, wave == 0 && mk_lane() == 0); } } while (0)
; __device__ __forceinline__ void xcd_barrier(const XcdBarrier& b, bool leader) {
;     asm volatile("s_waitcnt vmcnt(0)" ::: "memory");
;     __syncthreads();
;     if (leader) {
;         unsigned* bar = b.bar;
;         __builtin_amdgcn_s_waitcnt(0);
;         unsigned nloc = b.st[0], nx = b.st[1];
;         if (nloc == 0u) { xcd_barrier_complete(bar, b.x, nloc, nx); b.st[0] = nloc; b.st[1] = nx; }
;         const unsigned old = xb_add(&bar[XB_XSUB(b.x)], 1u);
;         const unsigned gen = old / nloc;
;         if (old + 1u == (gen + 1u) * nloc) {
;             __builtin_amdgcn_fence(__ATOMIC_RELEASE, "agent");
;             asm volatile("s_waitcnt vmcnt(0)" ::: "memory");
;             const unsigned og = xb_add(&bar[XB_TOP], 1u);
;             const unsigned tg = og / nx;
;             if (og + 1u == (tg + 1u) * nx) xb_add(&bar[XB_TOPGEN], 1u);
;             else XB_SPIN(xb_ld(&bar[XB_TOPGEN]) == tg, bar);
;             __builtin_amdgcn_fence(__ATOMIC_ACQUIRE, "agent");
;             xb_add(&bar[XB_XGEN(b.x)], 1u);
;             asm volatile("s_waitcnt vmcnt(0)" ::: "memory");
;         } else {
;             XB_SPIN(xb_ld(&bar[XB_XGEN(b.x)]) == gen, bar);
;             __builtin_amdgcn_fence(__ATOMIC_ACQUIRE, "agent");
;             asm volatile("s_waitcnt vmcnt(0)" ::: "memory");
;         }
;     }
;     __syncthreads();
; }
; __global__ void __launch_bounds__(NWAVES * 64, 2) mk_fwd(Params P) {
;     ...
;         for (int u = vcu * upc; u < (vcu + 1) * upc && u < 512; ++u) { const int bh = u >> 4, qblk = u & 15; xattn::unit(bh >> 2, bh & 3, qblk, CQ, CKb, CVT, CO, lds, wave); }
;     }
;     SEAM(6);
.LBB0_1150:
	s_waitcnt vmcnt(0)
	s_waitcnt vmcnt(0) lgkmcnt(0)
	s_barrier
	s_and_saveexec_b64 s[0:1], s[6:7]
	s_cbranch_execz .LBB0_1198
	v_readlane_b32 s8, v254, 2
	v_readlane_b32 s9, v254, 3
	s_and_b32 s2, s88, 7
	s_lshl_b32 s2, s2, 8
	s_add_u32 s2, s8, s2
	s_addc_u32 s3, s9, 0
	v_mov_b32_e32 v0, 0
	v_mov_b32_e32 v1, 1
	v_mov_b32_e32 v5, 0x1400
	global_load_dwordx4 v[6:9], v0, s[8:9] offset:768 sc1
	global_load_dwordx4 v[10:13], v0, s[8:9] offset:784 sc1
	global_atomic_add v5, v1, s[2:3] offset:128
	global_load_dword v3, v5, s[2:3] offset:128 sc1
	s_waitcnt vmcnt(2)
	v_add_u32_e32 v14, -1, v6
	v_and_b32_e32 v2, v14, v6
	v_add_u32_e32 v14, -1, v7
	v_and_or_b32 v2, v14, v7, v2
	v_add_u32_e32 v14, -1, v8
	v_and_or_b32 v2, v14, v8, v2
	v_add_u32_e32 v14, -1, v9
	v_and_or_b32 v2, v14, v9, v2
	v_add_u32_e32 v14, -1, v10
	v_and_or_b32 v2, v14, v10, v2
	v_add_u32_e32 v14, -1, v11
	v_and_or_b32 v2, v14, v11, v2
	v_add_u32_e32 v14, -1, v12
	v_and_or_b32 v2, v14, v12, v2
	v_add_u32_e32 v14, -1, v13
	v_and_or_b32 v2, v14, v13, v2
	v_cmp_ne_u32_e32 vcc, 0, v2
	s_cbranch_vccnz .Lmy_glob_k6
	v_mov_b32_e32 v4, 192
	s_waitcnt vmcnt(0)
	v_sub_u32_e32 v2, v3, v4
	v_cmp_gt_i32_e32 vcc, 0, v2
	s_cbranch_vccz .Lmy_done_k6
	s_mov_b32 s10, 0

; __device__ __forceinline__ unsigned xb_ld(unsigned* p)              { return __hip_atomic_load(p, __ATOMIC_RELAXED, __HIP_MEMORY_SCOPE_AGENT); }
; __device__ __forceinline__ unsigned xb_add(unsigned* p, unsigned v) { return __hip_atomic_fetch_add(p, v, __ATOMIC_RELAXED, __HIP_MEMORY_SCOPE_AGENT); }
; #define XB_SPIN(cond, bar) do { unsigned _sp = 0; while (cond) { __builtin_amdgcn_s_sleep(1); \
;     if ((++_sp & 255u) == 0u) { if (xb_ld(&(bar)[XB_TMO])) break; if (_sp > XB_SPIN_CAP) { atomicAdd(&(bar)[XB_TMO], 1u); break; } } } } while (0)
; #define SEAM(k) do { if (IN(k) && IN((k) + 1)) { xcd_barrier(bar, wave == 0 && mk_lane() == 0); } } while (0)
; __device__ __forceinline__ void xcd_barrier(const XcdBarrier& b, bool leader) {
;     asm volatile("s_waitcnt vmcnt(0)" ::: "memory");
;     __syncthreads();
;     if (leader) {
;         unsigned* bar = b.bar;
;         __builtin_amdgcn_s_waitcnt(0);
;         unsigned nloc = b.st[0], nx = b.st[1];
;         if (nloc == 0u) { xcd_barrier_complete(bar, b.x, nloc, nx); b.st[0] = nloc; b.st[1] = nx; }
;         const unsigned old = xb_add(&bar[XB_XSUB(b.x)], 1u);
;         const unsigned gen = old / nloc;
;         if (old + 1u == (gen + 1u) * nloc) {
;             __builtin_amdgcn_fence(__ATOMIC_RELEASE, "agent");
;             asm volatile("s_waitcnt vmcnt(0)" ::: "memory");
;             const unsigned og = xb_add(&bar[XB_TOP], 1u);
;             const unsigned tg = og / nx;
;             if (og + 1u == (tg + 1u) * nx) xb_add(&bar[XB_TOPGEN], 1u);
;             else XB_SPIN(xb_ld(&bar[XB_TOPGEN]) == tg, bar);
;             __builtin_amdgcn_fence(__ATOMIC_ACQUIRE, "agent");
;             xb_add(&bar[XB_XGEN(b.x)], 1u);
;             asm volatile("s_waitcnt vmcnt(0)" ::: "memory");
;         } else {
;             XB_SPIN(xb_ld(&bar[XB_XGEN(b.x)]) == gen, bar);
;             __builtin_amdgcn_fence(__ATOMIC_ACQUIRE, "agent");
;             asm volatile("s_waitcnt vmcnt(0)" ::: "memory");
;         }
;     }
;     __syncthreads();
; }
; __global__ void __launch_bounds__(NWAVES * 64, 2) mk_fwd(Params P) {
;     ...
;         pg8::EpiRes2<true, true> E{H1B, H2B, SS2};
;         pg8::gemm_phase<pg8::EpiRes2<true, true>, pg8::StaticOrder, true, true>(lds, g, S, E, wave); }
;     SEAM(7);
.LBB0_1241:
	s_waitcnt vmcnt(0)
	s_waitcnt vmcnt(0) lgkmcnt(0)
	s_barrier
	s_and_saveexec_b64 s[0:1], s[6:7]
	s_cbranch_execz .LBB0_1289
	v_readlane_b32 s8, v254, 2
	v_readlane_b32 s9, v254, 3
	s_and_b32 s2, s88, 7
	s_lshl_b32 s2, s2, 8
	s_add_u32 s2, s8, s2
	s_addc_u32 s3, s9, 0
	v_mov_b32_e32 v0, 0
	v_mov_b32_e32 v1, 1
	v_mov_b32_e32 v5, 0x1400
	global_load_dwordx4 v[6:9], v0, s[8:9] offset:768 sc1
	global_load_dwordx4 v[10:13], v0, s[8:9] offset:784 sc1
	global_atomic_add v5, v1, s[2:3] offset:128
	buffer_inv sc1
	global_load_dword v3, v5, s[2:3] offset:128 sc1
	s_waitcnt vmcnt(3)
	v_add_u32_e32 v14, -1, v6
	v_and_b32_e32 v2, v14, v6
	v_add_u32_e32 v14, -1, v7
	v_and_or_b32 v2, v14, v7, v2
	v_add_u32_e32 v14, -1, v8
	v_and_or_b32 v2, v14, v8, v2
	v_add_u32_e32 v14, -1, v9
	v_and_or_b32 v2, v14, v9, v2
	v_add_u32_e32 v14, -1, v10
	v_and_or_b32 v2, v14, v10, v2
	v_add_u32_e32 v14, -1, v11
	v_and_or_b32 v2, v14, v11, v2
	v_add_u32_e32 v14, -1, v12
	v_and_or_b32 v2, v14, v12, v2
	v_add_u32_e32 v14, -1, v13
	v_and_or_b32 v2, v14, v13, v2
	v_cmp_ne_u32_e32 vcc, 0, v2
	s_cbranch_vccnz .Lmy_glob_k7
	v_mov_b32_e32 v4, 224
	s_waitcnt vmcnt(0)
	v_sub_u32_e32 v2, v3, v4
	v_cmp_gt_i32_e32 vcc, 0, v2
	s_cbranch_vccz .Lmy_done_k7
	s_mov_b32 s10, 0

; #define LAS __attribute__((address_space(3)))
; __device__ __forceinline__ unsigned xb_ld(unsigned* p)              { return __hip_atomic_load(p, __ATOMIC_RELAXED, __HIP_MEMORY_SCOPE_AGENT); }
; __device__ __forceinline__ unsigned xb_add(unsigned* p, unsigned v) { return __hip_atomic_fetch_add(p, v, __ATOMIC_RELAXED, __HIP_MEMORY_SCOPE_AGENT); }
; #define XB_SPIN(cond, bar) do { unsigned _sp = 0; while (cond) { __builtin_amdgcn_s_sleep(1); \
;     if ((++_sp & 255u) == 0u) { if (xb_ld(&(bar)[XB_TMO])) break; if (_sp > XB_SPIN_CAP) { atomicAdd(&(bar)[XB_TMO], 1u); break; } } } } while (0)
; #define SEAM(k) do { if (IN(k) && IN((k) + 1)) { xcd_barrier(bar, wave == 0 && mk_lane() == 0); } } while (0)
; __device__ __forceinline__ void xcd_barrier(const XcdBarrier& b, bool leader) {
;     asm volatile("s_waitcnt vmcnt(0)" ::: "memory");
;     __syncthreads();
;     if (leader) {
;         unsigned* bar = b.bar;
;         __builtin_amdgcn_s_waitcnt(0);
;         unsigned nloc = b.st[0], nx = b.st[1];
;         if (nloc == 0u) { xcd_barrier_complete(bar, b.x, nloc, nx); b.st[0] = nloc; b.st[1] = nx; }
;         const unsigned old = xb_add(&bar[XB_XSUB(b.x)], 1u);
;         const unsigned gen = old / nloc;
;         if (old + 1u == (gen + 1u) * nloc) {
;             __builtin_amdgcn_fence(__ATOMIC_RELEASE, "agent");
;             asm volatile("s_waitcnt vmcnt(0)" ::: "memory");
;             const unsigned og = xb_add(&bar[XB_TOP], 1u);
;             const unsigned tg = og / nx;
;             if (og + 1u == (tg + 1u) * nx) xb_add(&bar[XB_TOPGEN], 1u);
;             else XB_SPIN(xb_ld(&bar[XB_TOPGEN]) == tg, bar);
;             __builtin_amdgcn_fence(__ATOMIC_ACQUIRE, "agent");
;             xb_add(&bar[XB_XGEN(b.x)], 1u);
;             asm volatile("s_waitcnt vmcnt(0)" ::: "memory");
;         } else {
;             XB_SPIN(xb_ld(&bar[XB_XGEN(b.x)]) == gen, bar);
;             __builtin_amdgcn_fence(__ATOMIC_ACQUIRE, "agent");
;             asm volatile("s_waitcnt vmcnt(0)" ::: "memory");
;         }
;     }
;     __syncthreads();
; }
; __global__ void __launch_bounds__(NWAVES * 64, 2) mk_fwd(Params P) {
;     ...
;         pg8::EpiRowScale<1> E{ZH, FF, SS2, EPS, 1.f, (const LAS int*)(lds + RING_BYTES + 1536), (const LAS float*)(lds + RING_BYTES + 2048)};
;         pg8::gemm_phase<pg8::EpiRowScale<1>, pg8::StaticOrder, true, true>(lds, g, S, E, wave); }
;     SEAM(8);
.LBB0_1391:
	s_waitcnt vmcnt(0)
	s_waitcnt vmcnt(0) lgkmcnt(0)
	s_barrier
	s_and_saveexec_b64 s[4:5], s[6:7]
	s_cbranch_execz .LBB0_1439
	v_readlane_b32 s8, v254, 2
	v_readlane_b32 s9, v254, 3
	s_and_b32 s2, s88, 7
	s_lshl_b32 s2, s2, 8
	s_add_u32 s2, s8, s2
	s_addc_u32 s3, s9, 0
	v_mov_b32_e32 v0, 0
	v_mov_b32_e32 v1, 1
	v_mov_b32_e32 v5, 0x1400
	global_load_dwordx4 v[6:9], v0, s[8:9] offset:768 sc1
	global_load_dwordx4 v[10:13], v0, s[8:9] offset:784 sc1
	global_atomic_add v5, v1, s[2:3] offset:128
	global_load_dword v3, v5, s[2:3] offset:128 sc1
	s_waitcnt vmcnt(2)
	v_add_u32_e32 v14, -1, v6
	v_and_b32_e32 v2, v14, v6
	v_add_u32_e32 v14, -1, v7
	v_and_or_b32 v2, v14, v7, v2
	v_add_u32_e32 v14, -1, v8
	v_and_or_b32 v2, v14, v8, v2
	v_add_u32_e32 v14, -1, v9
	v_and_or_b32 v2, v14, v9, v2
	v_add_u32_e32 v14, -1, v10
	v_and_or_b32 v2, v14, v10, v2
	v_add_u32_e32 v14, -1, v11
	v_and_or_b32 v2, v14, v11, v2
	v_add_u32_e32 v14, -1, v12
	v_and_or_b32 v2, v14, v12, v2
	v_add_u32_e32 v14, -1, v13
	v_and_or_b32 v2, v14, v13, v2
	v_cmp_ne_u32_e32 vcc, 0, v2
	s_cbranch_vccnz .Lmy_glob_k8
	v_mov_b32_e32 v4, 256
	s_waitcnt vmcnt(0)
	v_sub_u32_e32 v2, v3, v4
	v_cmp_gt_i32_e32 vcc, 0, v2
	s_cbranch_vccz .Lmy_done_k8
	s_mov_b32 s10, 0

; __device__ __forceinline__ unsigned xb_ld(unsigned* p)              { return __hip_atomic_load(p, __ATOMIC_RELAXED, __HIP_MEMORY_SCOPE_AGENT); }
; __device__ __forceinline__ unsigned xb_add(unsigned* p, unsigned v) { return __hip_atomic_fetch_add(p, v, __ATOMIC_RELAXED, __HIP_MEMORY_SCOPE_AGENT); }
; #define XB_SPIN(cond, bar) do { unsigned _sp = 0; while (cond) { __builtin_amdgcn_s_sleep(1); \
;     if ((++_sp & 255u) == 0u) { if (xb_ld(&(bar)[XB_TMO])) break; if (_sp > XB_SPIN_CAP) { atomicAdd(&(bar)[XB_TMO], 1u); break; } } } } while (0)
; #define SEAM(k) do { if (IN(k) && IN((k) + 1)) { xcd_barrier(bar, wave == 0 && mk_lane() == 0); } } while (0)
; __device__ __forceinline__ void xcd_barrier(const XcdBarrier& b, bool leader) {
;     asm volatile("s_waitcnt vmcnt(0)" ::: "memory");
;     __syncthreads();
;     if (leader) {
;         unsigned* bar = b.bar;
;         __builtin_amdgcn_s_waitcnt(0);
;         unsigned nloc = b.st[0], nx = b.st[1];
;         if (nloc == 0u) { xcd_barrier_complete(bar, b.x, nloc, nx); b.st[0] = nloc; b.st[1] = nx; }
;         const unsigned old = xb_add(&bar[XB_XSUB(b.x)], 1u);
;         const unsigned gen = old / nloc;
;         if (old + 1u == (gen + 1u) * nloc) {
;             __builtin_amdgcn_fence(__ATOMIC_RELEASE, "agent");
;             asm volatile("s_waitcnt vmcnt(0)" ::: "memory");
;             const unsigned og = xb_add(&bar[XB_TOP], 1u);
;             const unsigned tg = og / nx;
;             if (og + 1u == (tg + 1u) * nx) xb_add(&bar[XB_TOPGEN], 1u);
;             else XB_SPIN(xb_ld(&bar[XB_TOPGEN]) == tg, bar);
;             __builtin_amdgcn_fence(__ATOMIC_ACQUIRE, "agent");
;             xb_add(&bar[XB_XGEN(b.x)], 1u);
;             asm volatile("s_waitcnt vmcnt(0)" ::: "memory");
;         } else {
;             XB_SPIN(xb_ld(&bar[XB_XGEN(b.x)]) == gen, bar);
;             __builtin_amdgcn_fence(__ATOMIC_ACQUIRE, "agent");
;             asm volatile("s_waitcnt vmcnt(0)" ::: "memory");
;         }
;     }
;     __syncthreads();
; }
; __global__ void __launch_bounds__(NWAVES * 64, 2) mk_fwd(Params P) {
;     ...
;         pg8::EpiRes2<true, true> E{H2B, H1B  , SS3};
;         pg8::gemm_phase<pg8::EpiRes2<true, true>, pg8::StaticOrder, true, true>(lds, g, S, E, wave); }
;     SEAM(9);
.LBB0_1482:
	s_waitcnt vmcnt(0)
	s_waitcnt vmcnt(0) lgkmcnt(0)
	s_barrier
	s_and_saveexec_b64 s[0:1], s[6:7]
	s_cbranch_execz .LBB0_1530
	v_readlane_b32 s8, v254, 2
	v_readlane_b32 s9, v254, 3
	s_and_b32 s2, s88, 7
	s_lshl_b32 s2, s2, 8
	s_add_u32 s2, s8, s2
	s_addc_u32 s3, s9, 0
	v_mov_b32_e32 v0, 0
	v_mov_b32_e32 v1, 1
	v_mov_b32_e32 v5, 0x1400
	global_load_dwordx4 v[6:9], v0, s[8:9] offset:768 sc1
	global_load_dwordx4 v[10:13], v0, s[8:9] offset:784 sc1
	global_atomic_add v5, v1, s[2:3] offset:128
	global_load_dword v3, v5, s[2:3] offset:128 sc1
	s_waitcnt vmcnt(2)
	v_add_u32_e32 v14, -1, v6
	v_and_b32_e32 v2, v14, v6
	v_add_u32_e32 v14, -1, v7
	v_and_or_b32 v2, v14, v7, v2
	v_add_u32_e32 v14, -1, v8
	v_and_or_b32 v2, v14, v8, v2
	v_add_u32_e32 v14, -1, v9
	v_and_or_b32 v2, v14, v9, v2
	v_add_u32_e32 v14, -1, v10
	v_and_or_b32 v2, v14, v10, v2
	v_add_u32_e32 v14, -1, v11
	v_and_or_b32 v2, v14, v11, v2
	v_add_u32_e32 v14, -1, v12
	v_and_or_b32 v2, v14, v12, v2
	v_add_u32_e32 v14, -1, v13
	v_and_or_b32 v2, v14, v13, v2
	v_cmp_ne_u32_e32 vcc, 0, v2
	s_cbranch_vccnz .Lmy_glob_k9
	v_mov_b32_e32 v4, 288
	s_waitcnt vmcnt(0)
	v_sub_u32_e32 v2, v3, v4
	v_cmp_gt_i32_e32 vcc, 0, v2
	s_cbranch_vccz .Lmy_done_k9
	s_mov_b32 s10, 0
